# Up phase entry: the GEMM prologue's first eight LDS-DMA tile loads are issued before the rstd table fill (address set-up duplicated) so the fill overlaps the cold tile latency
# speedup vs baseline: 1.0012x; 1.0012x over previous
; #define LAS __attribute__((address_space(3)))
; #define PG8_STAGE(bufoff, gbase, voff) do { _Pragma("unroll") for (int _i = 0; _i < 2; ++_i) \
;         __builtin_amdgcn_global_load_lds((const unsigned*)((const char*)(gbase) + (voff)[_i]), (LAS unsigned*)(lds + (bufoff) + ldsw + _i * 8192), 16, 0, 0); } while (0)
; template <class Epi, class Sched>
; __device__ __forceinline__ void gemm_phase(LAS unsigned char* lds, const Gemm g, const Sched& S, const Epi& E) {
;     ...
;     for (int i = 0; i < 2; ++i) { int R, C; stage_rc(tid * 16 + i * 8192, R, C); const int Rb = Epi::PERM ? ((R & ~31) + perm32(R & 31)) : R;
;         voffA[i] = (unsigned)(R * g.lda + C) * 2u; voffB[i] = (unsigned)(Rb * g.ldb + C) * 2u; }
;     asm volatile("" : "+v"(voffA[0]), "+v"(voffA[1]), "+v"(voffB[0]), "+v"(voffB[1]));
;     const size_t kstep = (size_t)(BK * 2);
;     const size_t hstepA = (size_t)HALF * g.lda * 2, hstepB = (size_t)HALF * g.ldb * 2;
;     const size_t tstepA = 2 * hstepA, tstepB = 2 * hstepB;
;     const unsigned ldsw = (unsigned)wid * 1024u;
;     const int aoff = lds_byte(wr * 64 + fr, fq * 8), boff = lds_byte(wc * 32 + fr, fq * 8);
;     ...
;     Unit cur, nxt; int ui = 0;
;     if (!S.next(0, cur)) return;
;     f32x4 acc[2][2][4][2];
;     E.init(acc, cur, wr, wc, fr, fq);
;     bf16x8 At[4][2], B0[2][2], B1[2][2];
;     const char* cA = (const char*)g.A + (size_t)cur.pm * tstepA + (size_t)cur.pn * g.a_pn_off * 2; const char* cB = (const char*)g.Bt + (size_t)cur.pn * tstepB;
;     PG8_STAGE(PG8_SB(0, 0), cB, voffB); PG8_STAGE(PG8_SB(0, 1), cB + hstepB, voffB); PG8_STAGE(PG8_SA(0, 0), cA, voffA); PG8_STAGE(PG8_SA(0, 1), cA + hstepA, voffA);
; template <int MAXU, class Sched> __device__ __forceinline__ void fill_rstd(LAS float* rs, const float* ssqp, const Sched& S, bool by_pn) {
;     pg8::Unit u0; int tid = threadIdx.x; asm volatile("" : "+v"(tid));
;     if (S.next(0, u0)) {
;         f32x4 a[MAXU], b[MAXU]; bool have[MAXU];
; #pragma unroll
;         for (int i = 0; i < MAXU; ++i) {
;             pg8::Unit u; have[i] = S.next(i, u); if (!have[i]) u = u0;
;             const int row = 256 * (by_pn ? u.pn : u.pm) + (tid >> 1);
;             const f32x4* p = (const f32x4*)(ssqp + (size_t)row * 16 + (tid & 1) * 8);
;             a[i] = p[0]; b[i] = p[1];
.LBB0_178:
	s_xor_b64 s[8:9], s[18:19], -1
	s_mov_b64 s[0:1], -1
	v_writelane_b32 v248, s8, 29
	s_and_b64 vcc, exec, s[8:9]
	s_mov_b64 s[18:19], 0
	v_writelane_b32 v248, s9, 30
	s_cbranch_vccz .LBB0_318
	s_waitcnt vmcnt(0)
	v_cmp_ne_u32_e64 s[66:67], 1, v211
	s_nop 3
	v_mov_b32_e32 v2, v210
	s_mov_b32 s0, 0x1fffe0
	v_bfe_i32 v4, v2, 27, 1
	v_lshlrev_b32_e32 v1, 4, v2
	v_lshrrev_b32_e32 v4, 22, v4
	v_add_u32_e32 v4, v1, v4
	v_and_b32_e32 v4, 0xfffffc00, v4
	v_sub_u32_e32 v4, v1, v4
	v_ashrrev_i32_e32 v3, 31, v2
	v_lshrrev_b32_e32 v5, 4, v4
	v_lshrrev_b32_e32 v3, 26, v3
	v_bitop3_b32 v4, v5, v4, 32 bitop3:0x6c
	v_add_u32_e32 v3, v2, v3
	v_ashrrev_i32_e32 v6, 31, v4
	v_ashrrev_i32_e32 v3, 6, v3
	v_lshrrev_b32_e32 v6, 26, v6
	v_lshlrev_b32_e32 v5, 3, v3
	v_add_u32_e32 v6, v4, v6
	v_and_b32_e32 v5, -16, v5
	v_ashrrev_i32_e32 v7, 6, v6
	v_and_b32_e32 v6, 0xc0, v6
	v_add_u32_e32 v5, v7, v5
	v_sub_u32_e32 v4, v4, v6
	v_lshlrev_b32_e32 v3, 5, v3
	v_ashrrev_i16_sdwa v4, v213, sext(v4) dst_sel:DWORD dst_unused:UNUSED_PAD src0_sel:DWORD src1_sel:BYTE_0
	v_lshlrev_b32_e32 v6, 1, v5
	v_lshrrev_b32_e32 v8, 2, v5
	v_and_b32_e32 v7, 3, v7
	v_and_b32_e32 v3, 32, v3
	v_bfe_i32 v4, v4, 0, 16
	v_and_b32_e32 v6, 24, v6
	v_and_b32_e32 v8, 4, v8
	v_and_or_b32 v7, v5, s0, v7
	v_or3_b32 v6, v7, v8, v6
	v_add_lshl_u32 v3, v3, v4, 1
	v_add_u32_e32 v1, 0x2000, v1
	v_lshl_add_u32 v170, v5, 11, v3
	v_lshl_add_u32 v172, v6, 11, v3
	v_ashrrev_i32_e32 v3, 31, v1
	v_lshrrev_b32_e32 v3, 22, v3
	v_add_u32_e32 v3, v1, v3
	v_ashrrev_i32_e32 v3, 10, v3
	v_mul_i32_i24_e32 v4, 0x400, v3
	v_sub_u32_e32 v1, v1, v4
	v_lshrrev_b32_e32 v4, 4, v1
	v_bitop3_b32 v1, v4, v1, 32 bitop3:0x6c
	v_ashrrev_i32_e32 v5, 31, v1
	v_lshrrev_b32_e32 v5, 26, v5
	v_lshlrev_b32_e32 v4, 3, v3
	v_add_u32_e32 v5, v1, v5
	v_and_b32_e32 v4, -16, v4
	v_ashrrev_i32_e32 v6, 6, v5
	v_and_b32_e32 v5, 0xc0, v5
	v_add_u32_e32 v4, v6, v4
	v_sub_u32_e32 v1, v1, v5
	v_lshlrev_b32_e32 v3, 5, v3
	v_ashrrev_i16_sdwa v1, v213, sext(v1) dst_sel:DWORD dst_unused:UNUSED_PAD src0_sel:DWORD src1_sel:BYTE_0
	v_lshlrev_b32_e32 v5, 1, v4
	v_lshrrev_b32_e32 v7, 2, v4
	v_and_b32_e32 v6, 3, v6
	v_and_b32_e32 v3, 32, v3
	v_bfe_i32 v1, v1, 0, 16
	v_and_b32_e32 v5, 24, v5
	v_and_b32_e32 v7, 4, v7
	v_and_or_b32 v6, v4, s0, v6
	v_or3_b32 v5, v6, v7, v5
	v_add_lshl_u32 v1, v3, v1, 1
	v_readfirstlane_b32 s18, v2
	v_lshl_add_u32 v190, v4, 11, v1
	v_lshl_add_u32 v192, v5, 11, v1
	s_and_b64 vcc, exec, s[66:67]
	s_cbranch_vccnz .Lup_early_done
	s_ashr_i32 s20, s18, 6
	s_lshl_b32 s8, s20, 10
	s_add_i32 s9, s8, 0
	v_readlane_b32 s0, v248, 9
	s_add_i32 m0, s9, 0x10000
	v_readlane_b32 s1, v248, 10
	s_add_i32 s28, s9, 0x2000
	s_add_i32 s29, s9, 0x4000
	s_add_i32 s30, s9, 0x6000
	s_ashr_i32 s19, s18, 8
	s_nop 0
	global_load_lds_dwordx4 v172, s[0:1]
	s_add_i32 m0, s9, 0x12000
	s_nop 0
	global_load_lds_dwordx4 v192, s[0:1]
	v_readlane_b32 s0, v248, 7
	s_add_i32 m0, s9, 0x14000
	v_readlane_b32 s1, v248, 8
	s_nop 4
	global_load_lds_dwordx4 v172, s[0:1]
	s_add_i32 m0, s9, 0x16000
	s_cmp_eq_u32 s19, 1
	global_load_lds_dwordx4 v192, s[0:1]
	v_readlane_b32 s0, v250, 5
	s_mov_b32 m0, s9
	v_readlane_b32 s1, v250, 6
	s_nop 4
	global_load_lds_dwordx4 v170, s[0:1]
	s_mov_b32 m0, s28
	s_nop 0
	global_load_lds_dwordx4 v190, s[0:1]
	v_readlane_b32 s0, v250, 7
	s_mov_b32 m0, s29
	v_readlane_b32 s1, v250, 8
	s_nop 4
	global_load_lds_dwordx4 v170, s[0:1]
	s_mov_b32 m0, s30
	s_nop 0
	global_load_lds_dwordx4 v190, s[0:1]
.Lup_early_done:
	v_readlane_b32 s0, v251, 51
	v_readlane_b32 s1, v251, 52
	v_mov_b32_e32 v1, v210
	s_nop 1
	s_andn2_b64 vcc, exec, s[0:1]
	s_cbranch_vccnz .LBB0_223
	v_ashrrev_i32_e32 v91, 1, v1
	v_readlane_b32 s0, v252, 63
	v_lshlrev_b32_e32 v2, 5, v1
	v_and_b32_e32 v2, 32, v2
	v_add_u32_e32 v4, s0, v91
	s_waitcnt lgkmcnt(0)
	v_mov_b32_e32 v3, v0
	v_ashrrev_i32_e32 v5, 31, v4
	v_lshl_add_u64 v[2:3], s[6:7], 0, v[2:3]
	v_lshlrev_b64 v[4:5], 6, v[4:5]
	v_lshl_add_u64 v[4:5], v[2:3], 0, v[4:5]
	global_load_dwordx4 v[82:85], v[4:5], off offset:16
	global_load_dwordx4 v[86:89], v[4:5], off
	v_readlane_b32 s0, v249, 7
	v_readlane_b32 s1, v249, 8
	s_andn2_b64 vcc, exec, s[0:1]
	v_readlane_b32 s0, v250, 3
	v_readlane_b32 s1, v250, 4
	s_cbranch_vccnz .LBB0_182
	v_readlane_b32 s0, v250, 25

; #define PG8_STAGE(bufoff, gbase, voff) do { _Pragma("unroll") for (int _i = 0; _i < 2; ++_i) \
;         __builtin_amdgcn_global_load_lds((const unsigned*)((const char*)(gbase) + (voff)[_i]), (LAS unsigned*)(lds + (bufoff) + ldsw + _i * 8192), 16, 0, 0); } while (0)
; #define PG8_BAR __builtin_amdgcn_s_barrier()
;     __device__ __forceinline__ void init(f32x4 (&acc)[2][2][4][2], const pg8::Unit&, int, int, int, int) const { acc_zero(acc); }
;     __device__ __forceinline__ void init(f32x4 (&acc)[2][2][4][2], const pg8::Unit&, int, int, int, int) const { acc_zero(acc); }
;     __device__ __forceinline__ void init(f32x4 (&acc)[2][2][4][2], const pg8::Unit&, int, int, int, int) const { acc_zero(acc); }
;     __device__ __forceinline__ void init(f32x4 (&acc)[2][2][4][2], const pg8::Unit&, int, int, int, int) const { acc_zero(acc); }
; template <class Epi, class Sched>
; __device__ __forceinline__ void gemm_phase(LAS unsigned char* lds, const Gemm g, const Sched& S, const Epi& E) {
;     ...
;     for (int i = 0; i < 2; ++i) { int R, C; stage_rc(tid * 16 + i * 8192, R, C); const int Rb = Epi::PERM ? ((R & ~31) + perm32(R & 31)) : R;
;         voffA[i] = (unsigned)(R * g.lda + C) * 2u; voffB[i] = (unsigned)(Rb * g.ldb + C) * 2u; }
;     asm volatile("" : "+v"(voffA[0]), "+v"(voffA[1]), "+v"(voffB[0]), "+v"(voffB[1]));
;     const size_t kstep = (size_t)(BK * 2);
;     const size_t hstepA = (size_t)HALF * g.lda * 2, hstepB = (size_t)HALF * g.ldb * 2;
;     const size_t tstepA = 2 * hstepA, tstepB = 2 * hstepB;
;     const unsigned ldsw = (unsigned)wid * 1024u;
;     const int aoff = lds_byte(wr * 64 + fr, fq * 8), boff = lds_byte(wc * 32 + fr, fq * 8);
;     ...
;     Unit cur, nxt; int ui = 0;
;     if (!S.next(0, cur)) return;
;     f32x4 acc[2][2][4][2];
;     E.init(acc, cur, wr, wc, fr, fq);
;     bf16x8 At[4][2], B0[2][2], B1[2][2];
;     const char* cA = (const char*)g.A + (size_t)cur.pm * tstepA + (size_t)cur.pn * g.a_pn_off * 2; const char* cB = (const char*)g.Bt + (size_t)cur.pn * tstepB;
;     PG8_STAGE(PG8_SB(0, 0), cB, voffB); PG8_STAGE(PG8_SB(0, 1), cB + hstepB, voffB); PG8_STAGE(PG8_SA(0, 0), cA, voffA); PG8_STAGE(PG8_SA(0, 1), cA + hstepA, voffA);
;     if (wr == 1) PG8_BAR;
.LBB0_223:
	v_mov_b32_e32 v2, v210
	s_waitcnt lgkmcnt(0)
	s_barrier
	s_mov_b32 s0, 0x1fffe0
	v_bfe_i32 v4, v2, 27, 1
	v_lshlrev_b32_e32 v1, 4, v2
	v_lshrrev_b32_e32 v4, 22, v4
	v_add_u32_e32 v4, v1, v4
	v_and_b32_e32 v4, 0xfffffc00, v4
	v_sub_u32_e32 v4, v1, v4
	v_ashrrev_i32_e32 v3, 31, v2
	v_lshrrev_b32_e32 v5, 4, v4
	v_lshrrev_b32_e32 v3, 26, v3
	v_bitop3_b32 v4, v5, v4, 32 bitop3:0x6c
	v_add_u32_e32 v3, v2, v3
	v_ashrrev_i32_e32 v6, 31, v4
	v_ashrrev_i32_e32 v3, 6, v3
	v_lshrrev_b32_e32 v6, 26, v6
	v_lshlrev_b32_e32 v5, 3, v3
	v_add_u32_e32 v6, v4, v6
	v_and_b32_e32 v5, -16, v5
	v_ashrrev_i32_e32 v7, 6, v6
	v_and_b32_e32 v6, 0xc0, v6
	v_add_u32_e32 v5, v7, v5
	v_sub_u32_e32 v4, v4, v6
	v_lshlrev_b32_e32 v3, 5, v3
	v_ashrrev_i16_sdwa v4, v213, sext(v4) dst_sel:DWORD dst_unused:UNUSED_PAD src0_sel:DWORD src1_sel:BYTE_0
	v_lshlrev_b32_e32 v6, 1, v5
	v_lshrrev_b32_e32 v8, 2, v5
	v_and_b32_e32 v7, 3, v7
	v_and_b32_e32 v3, 32, v3
	v_bfe_i32 v4, v4, 0, 16
	v_and_b32_e32 v6, 24, v6
	v_and_b32_e32 v8, 4, v8
	v_and_or_b32 v7, v5, s0, v7
	v_or3_b32 v6, v7, v8, v6
	v_add_lshl_u32 v3, v3, v4, 1
	v_add_u32_e32 v1, 0x2000, v1
	v_lshl_add_u32 v170, v5, 11, v3
	v_lshl_add_u32 v172, v6, 11, v3
	v_ashrrev_i32_e32 v3, 31, v1
	v_lshrrev_b32_e32 v3, 22, v3
	v_add_u32_e32 v3, v1, v3
	v_ashrrev_i32_e32 v3, 10, v3
	v_mul_i32_i24_e32 v4, 0x400, v3
	v_sub_u32_e32 v1, v1, v4
	v_lshrrev_b32_e32 v4, 4, v1
	v_bitop3_b32 v1, v4, v1, 32 bitop3:0x6c
	v_ashrrev_i32_e32 v5, 31, v1
	v_lshrrev_b32_e32 v5, 26, v5
	v_lshlrev_b32_e32 v4, 3, v3
	v_add_u32_e32 v5, v1, v5
	v_and_b32_e32 v4, -16, v4
	v_ashrrev_i32_e32 v6, 6, v5
	v_and_b32_e32 v5, 0xc0, v5
	v_add_u32_e32 v4, v6, v4
	v_sub_u32_e32 v1, v1, v5
	v_lshlrev_b32_e32 v3, 5, v3
	v_ashrrev_i16_sdwa v1, v213, sext(v1) dst_sel:DWORD dst_unused:UNUSED_PAD src0_sel:DWORD src1_sel:BYTE_0
	v_lshlrev_b32_e32 v5, 1, v4
	v_lshrrev_b32_e32 v7, 2, v4
	v_and_b32_e32 v6, 3, v6
	v_and_b32_e32 v3, 32, v3
	v_bfe_i32 v1, v1, 0, 16
	v_and_b32_e32 v5, 24, v5
	v_and_b32_e32 v7, 4, v7
	v_and_or_b32 v6, v4, s0, v6
	v_or3_b32 v5, v6, v7, v5
	v_add_lshl_u32 v1, v3, v1, 1
	v_readfirstlane_b32 s18, v2
	v_lshl_add_u32 v190, v4, 11, v1
	v_lshl_add_u32 v192, v5, 11, v1
	s_and_b64 vcc, exec, s[66:67]
	s_cbranch_vccnz .LBB0_247
	s_ashr_i32 s20, s18, 6
	s_lshl_b32 s8, s20, 10
	s_add_i32 s9, s8, 0
	v_readlane_b32 s0, v248, 9
	s_add_i32 m0, s9, 0x10000
	v_readlane_b32 s1, v248, 10
	s_add_i32 s28, s9, 0x2000
	s_add_i32 s29, s9, 0x4000
	s_add_i32 s30, s9, 0x6000
	s_ashr_i32 s19, s18, 8
	s_nop 0
	s_add_i32 m0, s9, 0x12000
	s_nop 0
	v_readlane_b32 s0, v248, 7
	s_add_i32 m0, s9, 0x14000
	v_readlane_b32 s1, v248, 8
	s_nop 4
	s_add_i32 m0, s9, 0x16000
	s_cmp_eq_u32 s19, 1
	v_readlane_b32 s0, v250, 5
	s_mov_b32 m0, s9
	v_readlane_b32 s1, v250, 6
	s_nop 4
	s_mov_b32 m0, s28
	s_nop 0
	v_readlane_b32 s0, v250, 7
	s_mov_b32 m0, s29
	v_readlane_b32 s1, v250, 8
	s_nop 4
	s_mov_b32 m0, s30
	s_nop 0
	s_cselect_b64 s[0:1], -1, 0
	s_cmp_lg_u32 s19, 1
	s_cbranch_scc1 .LBB0_226
	s_barrier
